# v83 + streaming hint on the scan's raw value-row loads (publisher waves) and per-step output stores
# baseline (speedup 1.0000x reference)
.LBB0_457:
	v_lshl_add_u64 v[188:189], s[66:67], 0, v[170:171]
	s_mov_b32 s33, 0x15704000
	v_add_co_u32_e32 v88, vcc, s33, v188
	v_lshl_add_u64 v[184:185], s[66:67], 0, v[166:167]
	s_nop 0
	v_addc_co_u32_e32 v89, vcc, 0, v189, vcc
	v_add_co_u32_e32 v90, vcc, s82, v184
	v_lshl_add_u64 v[186:187], s[66:67], 0, v[168:169]
	s_nop 0
	v_addc_co_u32_e32 v91, vcc, 0, v185, vcc
	v_add_co_u32_e32 v92, vcc, s83, v184
	global_load_dwordx4 v[112:115], v[88:89], off
	global_load_dwordx4 v[116:119], v[90:91], off
	global_load_dwordx4 v[120:123], v[90:91], off offset:1024
	global_load_dwordx4 v[124:127], v[90:91], off offset:2048
	v_addc_co_u32_e32 v93, vcc, 0, v185, vcc
	global_load_dwordx4 v[128:131], v[90:91], off offset:3072
	global_load_dwordx4 v[100:103], v[92:93], off
	global_load_dwordx4 v[96:99], v[92:93], off offset:1024
	s_nop 0
	global_load_dwordx4 v[88:91], v[92:93], off offset:2048
	s_nop 0
	global_load_dwordx4 v[92:95], v[92:93], off offset:3072
	s_nop 0
	global_load_dwordx4 v[108:111], v[186:187], off offset:-1024
	global_load_dwordx4 v[104:107], v[186:187], off offset:-960
	s_add_i32 s96, s18, 3
	s_and_b32 s33, s96, 1
	s_lshl_b32 s54, s33, 15
	s_lshl_b32 s33, s33, 11
	s_add_i32 s33, s69, s33
	v_add_u32_e32 v201, s33, v163
	ds_read_b64_tr_b16 v[206:207], v201
	v_add_u32_e32 v202, 0x80, v201
	ds_read_b64_tr_b16 v[208:209], v202
	v_add_u32_e32 v203, 0x400, v201
	ds_read_b64_tr_b16 v[210:211], v203
	v_add_u32_e32 v204, 0x480, v201
	ds_read_b64_tr_b16 v[212:213], v204
	s_waitcnt lgkmcnt(0)
	v_cvt_pk_bf16_f32 v214, v132, v133
	v_cvt_pk_bf16_f32 v215, v134, v135
	v_cvt_pk_bf16_f32 v216, v136, v137
	v_cvt_pk_bf16_f32 v217, v138, v139
	s_add_i32 s33, s54, 0
	s_waitcnt vmcnt(31)
	v_mfma_f32_16x16x32_bf16 v[44:47], v[44:47], v[214:217], 0
	s_add_i32 s54, s68, s33
	s_add_i32 s18, s18, 4
	s_and_b32 s18, s18, 1
	s_waitcnt vmcnt(30)
	v_mfma_f32_16x16x32_bf16 v[52:55], v[52:55], v[214:217], 0
	s_waitcnt vmcnt(29)
	v_mfma_f32_16x16x32_bf16 v[28:31], v[28:31], v[214:217], 0
	s_waitcnt vmcnt(28)
	v_mfma_f32_16x16x32_bf16 v[20:23], v[20:23], v[214:217], 0
	v_cndmask_b32_e64 v215, v211, v207, s[4:5]
	v_cndmask_b32_e64 v214, v210, v206, s[4:5]
	v_cndmask_b32_e64 v217, v213, v209, s[4:5]
	v_cndmask_b32_e64 v216, v212, v208, s[4:5]
	s_nop 1
	v_mfma_f32_16x16x32_bf16 v[0:3], v[0:3], v[214:217], 0
	v_lshlrev_b32_e32 v215, 2, v149
	v_add_u32_e32 v205, s54, v215
	s_nop 5
	v_cndmask_b32_e64 v182, 0, v0, s[6:7]
	v_add_f32_e32 v44, v44, v182
	v_cndmask_b32_e64 v182, 0, v1, s[6:7]
	v_add_f32_e32 v45, v45, v182
	v_cndmask_b32_e64 v182, 0, v2, s[6:7]
	v_add_f32_e32 v46, v46, v182
	v_cndmask_b32_e64 v182, 0, v3, s[6:7]
	v_add_f32_e32 v47, v47, v182
	v_cndmask_b32_e64 v182, 0, v0, s[8:9]
	v_add_f32_e32 v52, v52, v182
	v_cndmask_b32_e64 v182, 0, v1, s[8:9]
	v_add_f32_e32 v53, v53, v182
	v_cndmask_b32_e64 v182, 0, v2, s[8:9]
	v_add_f32_e32 v54, v54, v182
	v_cndmask_b32_e64 v182, 0, v3, s[8:9]
	v_add_f32_e32 v55, v55, v182
	v_cndmask_b32_e64 v182, 0, v0, s[10:11]
	v_add_f32_e32 v28, v28, v182
	v_cndmask_b32_e64 v182, 0, v1, s[10:11]
	v_add_f32_e32 v29, v29, v182
	v_cndmask_b32_e64 v182, 0, v2, s[10:11]
	v_add_f32_e32 v30, v30, v182
	v_cndmask_b32_e64 v182, 0, v3, s[10:11]
	v_cndmask_b32_e64 v0, 0, v0, s[12:13]
	v_add_f32_e32 v31, v31, v182
	v_add_f32_e32 v182, v20, v0
	v_cndmask_b32_e64 v0, 0, v1, s[12:13]
	v_add_f32_e32 v183, v21, v0
	v_cndmask_b32_e64 v0, 0, v2, s[12:13]
	v_add_f32_e32 v200, v22, v0
	v_cndmask_b32_e64 v0, 0, v3, s[12:13]
	v_add_f32_e32 v214, v23, v0
	s_waitcnt vmcnt(23)
	v_pk_mul_f32 v[2:3], v[134:135], v[42:43]
	v_pk_mul_f32 v[0:1], v[132:133], v[40:41]
	s_waitcnt vmcnt(22)
	v_pk_mul_f32 v[22:23], v[138:139], v[38:39]
	v_pk_mul_f32 v[20:21], v[136:137], v[36:37]
	v_mfma_f32_16x16x32_bf16 v[0:3], v[16:19], v[206:209], v[0:3]
	ds_write2st64_b32 v205, v44, v45 offset1:1
	ds_write2st64_b32 v205, v46, v47 offset0:2 offset1:3
	ds_write2st64_b32 v205, v52, v53 offset0:4 offset1:5
	ds_write2st64_b32 v205, v54, v55 offset0:6 offset1:7
	ds_write2st64_b32 v205, v28, v29 offset0:8 offset1:9
	ds_write2st64_b32 v205, v30, v31 offset0:10 offset1:11
	ds_write2st64_b32 v205, v182, v183 offset0:12 offset1:13
	ds_write2st64_b32 v205, v200, v214 offset0:14 offset1:15
	v_lshlrev_b32_e32 v214, 2, v190
	v_add_u32_e32 v200, s33, v214
	v_mfma_f32_16x16x32_bf16 v[132:135], v[12:15], v[210:213], v[0:3]
	s_waitcnt lgkmcnt(0)
	s_barrier
	v_mfma_f32_16x16x32_bf16 v[0:3], v[4:7], v[206:209], v[20:23]
	v_lshl_add_u64 v[182:183], s[66:67], 0, v[180:181]
	s_mov_b32 s33, 0x15706000
	v_mfma_f32_16x16x32_bf16 v[136:139], v[8:11], v[210:213], v[0:3]
	s_nop 4
	ds_read2st64_b64 v[0:3], v200 offset1:8
	ds_read2st64_b64 v[220:223], v200 offset0:16 offset1:24
	ds_read2st64_b64 v[224:227], v200 offset0:32 offset1:40
	ds_read2st64_b64 v[228:231], v200 offset0:48 offset1:56
	s_waitcnt lgkmcnt(3)
	v_add_f32_e32 v0, 0, v0
	v_add_f32_e32 v1, 0, v1
	v_add_f32_e32 v4, v0, v2
	v_add_f32_e32 v5, v1, v3
	s_waitcnt lgkmcnt(2)
	v_add_f32_e32 v0, v4, v220
	v_add_f32_e32 v1, v5, v221
	v_add_f32_e32 v4, v0, v222
	v_add_f32_e32 v5, v1, v223
	s_waitcnt lgkmcnt(1)
	v_add_f32_e32 v0, v4, v224
	v_add_f32_e32 v1, v5, v225
	v_add_f32_e32 v4, v0, v226
	v_add_f32_e32 v5, v1, v227
	s_waitcnt lgkmcnt(0)
	v_add_f32_e32 v0, v4, v228
	v_add_f32_e32 v1, v5, v229
	v_add_f32_e32 v0, v0, v230
	v_add_f32_e32 v1, v1, v231
	v_cvt_pk_bf16_f32 v2, v0, v1
	v_add_co_u32_e32 v0, vcc, s84, v182
	s_nop 1
	v_addc_co_u32_e32 v1, vcc, 0, v183, vcc
	global_store_dword v[0:1], v2, off nt
	v_add_co_u32_e32 v0, vcc, s33, v188
	s_lshl_b32 s33, s18, 15
	s_nop 0
	v_addc_co_u32_e32 v1, vcc, 0, v189, vcc
	v_add_co_u32_e32 v4, vcc, s85, v184
	global_load_dwordx4 v[0:3], v[0:1], off
	s_nop 0
	v_addc_co_u32_e32 v5, vcc, 0, v185, vcc
	v_add_co_u32_e32 v8, vcc, s86, v184
	global_load_dwordx4 v[44:47], v[4:5], off
	global_load_dwordx4 v[52:55], v[4:5], off offset:1024
	global_load_dwordx4 v[28:31], v[4:5], off offset:2048
	global_load_dwordx4 v[20:23], v[4:5], off offset:3072
	v_addc_co_u32_e32 v9, vcc, 0, v185, vcc
	global_load_dwordx4 v[16:19], v[8:9], off
	global_load_dwordx4 v[12:15], v[8:9], off offset:1024
	global_load_dwordx4 v[4:7], v[8:9], off offset:2048
	s_nop 0
	global_load_dwordx4 v[8:11], v[8:9], off offset:3072
	s_nop 0
	global_load_dwordx4 v[40:43], v[186:187], off
	global_load_dwordx4 v[36:39], v[186:187], off offset:64
	s_lshl_b32 s18, s18, 11
	s_add_i32 s18, s69, s18
	v_add_u32_e32 v188, s18, v163
	ds_read_b64_tr_b16 v[184:185], v188
	v_add_u32_e32 v186, 0x80, v188
	ds_read_b64_tr_b16 v[186:187], v186
	v_add_u32_e32 v189, 0x400, v188
	ds_read_b64_tr_b16 v[206:207], v189
	v_add_u32_e32 v188, 0x480, v188
	ds_read_b64_tr_b16 v[208:209], v188
	s_waitcnt lgkmcnt(0)
	v_cvt_pk_bf16_f32 v210, v132, v133
	v_cvt_pk_bf16_f32 v211, v134, v135
	v_cvt_pk_bf16_f32 v212, v136, v137
	v_cvt_pk_bf16_f32 v213, v138, v139
	s_add_i32 s18, s33, 0
	s_waitcnt vmcnt(32)
	v_mfma_f32_16x16x32_bf16 v[72:75], v[72:75], v[210:213], 0
	s_add_i32 s33, s68, s18
	s_waitcnt vmcnt(31)
	v_mfma_f32_16x16x32_bf16 v[76:79], v[76:79], v[210:213], 0
	s_waitcnt vmcnt(30)
	v_mfma_f32_16x16x32_bf16 v[80:83], v[80:83], v[210:213], 0
	s_waitcnt vmcnt(29)
	v_mfma_f32_16x16x32_bf16 v[84:87], v[84:87], v[210:213], 0
	v_cndmask_b32_e64 v211, v207, v185, s[4:5]
	v_cndmask_b32_e64 v210, v206, v184, s[4:5]
	v_cndmask_b32_e64 v213, v209, v187, s[4:5]
	v_cndmask_b32_e64 v212, v208, v186, s[4:5]
	s_nop 1
	v_mfma_f32_16x16x32_bf16 v[60:63], v[60:63], v[210:213], 0
	s_nop 7
	v_cndmask_b32_e64 v188, 0, v60, s[6:7]
	v_add_f32_e32 v72, v72, v188
	v_cndmask_b32_e64 v188, 0, v61, s[6:7]
	v_add_f32_e32 v73, v73, v188
	v_cndmask_b32_e64 v188, 0, v62, s[6:7]
	v_add_f32_e32 v74, v74, v188
	v_cndmask_b32_e64 v188, 0, v63, s[6:7]
	v_add_f32_e32 v75, v75, v188
	v_cndmask_b32_e64 v188, 0, v60, s[8:9]
	v_add_f32_e32 v76, v76, v188
	v_cndmask_b32_e64 v188, 0, v61, s[8:9]
	v_add_f32_e32 v77, v77, v188
	v_cndmask_b32_e64 v188, 0, v62, s[8:9]
	v_add_f32_e32 v78, v78, v188
	v_cndmask_b32_e64 v188, 0, v63, s[8:9]
	v_add_f32_e32 v79, v79, v188
	v_cndmask_b32_e64 v188, 0, v60, s[10:11]
	v_cndmask_b32_e64 v60, 0, v60, s[12:13]
	v_add_f32_e32 v84, v84, v60
	v_cndmask_b32_e64 v60, 0, v61, s[12:13]
	v_add_f32_e32 v80, v80, v188
	v_cndmask_b32_e64 v188, 0, v61, s[10:11]
	v_add_f32_e32 v85, v85, v60
	v_cndmask_b32_e64 v60, 0, v62, s[12:13]
	v_add_f32_e32 v81, v81, v188
	v_cndmask_b32_e64 v188, 0, v62, s[10:11]
	v_add_f32_e32 v86, v86, v60
	v_cndmask_b32_e64 v60, 0, v63, s[12:13]
	v_add_f32_e32 v82, v82, v188
	v_cndmask_b32_e64 v188, 0, v63, s[10:11]
	v_add_f32_e32 v87, v87, v60
	s_waitcnt vmcnt(24)
	v_pk_mul_f32 v[62:63], v[66:67], v[134:135]
	v_pk_mul_f32 v[60:61], v[64:65], v[132:133]
	s_waitcnt vmcnt(23)
	v_pk_mul_f32 v[66:67], v[70:71], v[138:139]
	v_pk_mul_f32 v[64:65], v[68:69], v[136:137]
	v_add_f32_e32 v83, v83, v188
	v_mfma_f32_16x16x32_bf16 v[56:59], v[56:59], v[184:187], v[60:63]
	v_mfma_f32_16x16x32_bf16 v[24:27], v[24:27], v[184:187], v[64:67]
	v_mfma_f32_16x16x32_bf16 v[136:139], v[32:35], v[206:209], v[24:27]
	v_add_u32_e32 v32, s18, v214
	s_min_u32 s18, s96, 59
	s_nop 4
	v_add_u32_e32 v24, s33, v215
	ds_write2st64_b32 v24, v72, v73 offset1:1
	ds_write2st64_b32 v24, v74, v75 offset0:2 offset1:3
	ds_write2st64_b32 v24, v76, v77 offset0:4 offset1:5
	ds_write2st64_b32 v24, v78, v79 offset0:6 offset1:7
	ds_write2st64_b32 v24, v80, v81 offset0:8 offset1:9
	ds_write2st64_b32 v24, v82, v83 offset0:10 offset1:11
	ds_write2st64_b32 v24, v84, v85 offset0:12 offset1:13
	ds_write2st64_b32 v24, v86, v87 offset0:14 offset1:15
	s_waitcnt lgkmcnt(0)
	s_barrier
	ds_read2st64_b64 v[24:27], v32 offset1:8
	ds_read2st64_b64 v[220:223], v32 offset0:16 offset1:24
	ds_read2st64_b64 v[224:227], v32 offset0:32 offset1:40
	ds_read2st64_b64 v[228:231], v32 offset0:48 offset1:56
	s_add_i32 s33, s18, 4
	s_lshl_b32 s18, s33, 13
	v_mfma_f32_16x16x32_bf16 v[132:135], v[48:51], v[206:209], v[56:59]
	s_waitcnt lgkmcnt(3)
	v_add_f32_e32 v24, 0, v24
	v_add_f32_e32 v25, 0, v25
	v_add_f32_e32 v33, v24, v26
	v_add_f32_e32 v34, v25, v27
	s_waitcnt lgkmcnt(2)
	v_add_f32_e32 v24, v33, v220
	v_add_f32_e32 v25, v34, v221
	v_add_f32_e32 v33, v24, v222
	v_add_f32_e32 v34, v25, v223
	s_waitcnt lgkmcnt(1)
	v_add_f32_e32 v24, v33, v224
	v_add_f32_e32 v25, v34, v225
	v_add_f32_e32 v33, v24, v226
	v_add_f32_e32 v34, v25, v227
	s_waitcnt lgkmcnt(0)
	v_add_f32_e32 v24, v33, v228
	v_add_f32_e32 v25, v34, v229
	v_add_f32_e32 v24, v24, v230
	v_add_f32_e32 v25, v25, v231
	v_cvt_pk_bf16_f32 v26, v24, v25
	v_add_co_u32_e32 v24, vcc, s87, v182
	s_nop 1
	v_addc_co_u32_e32 v25, vcc, 0, v183, vcc
	global_store_dword v[24:25], v26, off nt
	v_lshl_add_u64 v[24:25], v[172:173], 0, s[18:19]
	s_lshl_b32 s18, s33, 15
	global_load_dwordx4 v[60:63], v[24:25], off
	v_lshl_add_u64 v[24:25], v[174:175], 0, s[18:19]
	v_lshl_add_u64 v[32:33], v[176:177], 0, s[18:19]
	global_load_dwordx4 v[72:75], v[24:25], off
	global_load_dwordx4 v[76:79], v[24:25], off offset:1024
	global_load_dwordx4 v[80:83], v[24:25], off offset:2048
	global_load_dwordx4 v[84:87], v[24:25], off offset:3072
	global_load_dwordx4 v[56:59], v[32:33], off
	global_load_dwordx4 v[48:51], v[32:33], off offset:1024
	s_nop 0
	global_load_dwordx4 v[24:27], v[32:33], off offset:2048
	s_nop 0
	global_load_dwordx4 v[32:35], v[32:33], off offset:3072
	s_lshl_b32 s18, s33, 10
	v_lshl_add_u64 v[68:69], v[178:179], 0, s[18:19]
	global_load_dwordx4 v[64:67], v[68:69], off
	s_nop 0
	global_load_dwordx4 v[68:71], v[68:69], off offset:64
	ds_read_b64_tr_b16 v[184:185], v201
	ds_read_b64_tr_b16 v[186:187], v202
	ds_read_b64_tr_b16 v[206:207], v203
	ds_read_b64_tr_b16 v[208:209], v204
	s_waitcnt lgkmcnt(0)
	v_cvt_pk_bf16_f32 v210, v132, v133
	v_cvt_pk_bf16_f32 v211, v134, v135
	v_cvt_pk_bf16_f32 v212, v136, v137
	v_cvt_pk_bf16_f32 v213, v138, v139
	s_waitcnt vmcnt(24)
	v_pk_mul_f32 v[106:107], v[106:107], v[138:139]
	v_mfma_f32_16x16x32_bf16 v[116:119], v[116:119], v[210:213], 0
	v_mul_f32_e64 v104, v104, v136
	v_mul_f32_e64 v105, v105, v137
	v_pk_mul_f32 v[110:111], v[110:111], v[134:135]
	v_pk_mul_f32 v[108:109], v[108:109], v[132:133]
	v_mfma_f32_16x16x32_bf16 v[120:123], v[120:123], v[210:213], 0
	s_mov_b64 s[54:55], 0x6000
	v_lshl_add_u64 v[180:181], v[180:181], 0, s[42:43]
	v_lshl_add_u64 v[166:167], v[166:167], 0, s[48:49]
	v_mfma_f32_16x16x32_bf16 v[124:127], v[124:127], v[210:213], 0
	v_lshl_add_u64 v[168:169], v[168:169], 0, s[50:51]
	v_lshl_add_u64 v[170:171], v[170:171], 0, s[54:55]
	s_cmp_lt_u32 s96, 60
	v_mfma_f32_16x16x32_bf16 v[128:131], v[128:131], v[210:213], 0
	v_cndmask_b32_e64 v211, v207, v185, s[4:5]
	v_cndmask_b32_e64 v210, v206, v184, s[4:5]
	v_cndmask_b32_e64 v213, v209, v187, s[4:5]
	v_cndmask_b32_e64 v212, v208, v186, s[4:5]
	v_mfma_f32_16x16x32_bf16 v[88:91], v[88:91], v[184:187], v[104:107]
	s_mov_b32 s18, s96
	v_mfma_f32_16x16x32_bf16 v[112:115], v[112:115], v[210:213], 0
	v_mfma_f32_16x16x32_bf16 v[136:139], v[92:95], v[206:209], v[88:91]
	v_mfma_f32_16x16x32_bf16 v[100:103], v[100:103], v[184:187], v[108:111]
	s_nop 5
	v_cndmask_b32_e64 v188, 0, v112, s[6:7]
	v_add_f32_e32 v116, v116, v188
	v_cndmask_b32_e64 v188, 0, v113, s[6:7]
	v_add_f32_e32 v117, v117, v188
	v_cndmask_b32_e64 v188, 0, v114, s[6:7]
	v_add_f32_e32 v118, v118, v188
	v_cndmask_b32_e64 v188, 0, v115, s[6:7]
	v_add_f32_e32 v119, v119, v188
	v_cndmask_b32_e64 v188, 0, v112, s[8:9]
	v_add_f32_e32 v120, v120, v188
	v_cndmask_b32_e64 v188, 0, v113, s[8:9]
	v_add_f32_e32 v121, v121, v188
	v_cndmask_b32_e64 v188, 0, v114, s[8:9]
	v_add_f32_e32 v122, v122, v188
	v_cndmask_b32_e64 v188, 0, v115, s[8:9]
	v_add_f32_e32 v123, v123, v188
	v_cndmask_b32_e64 v188, 0, v112, s[10:11]
	v_add_f32_e32 v124, v124, v188
	v_cndmask_b32_e64 v188, 0, v113, s[10:11]
	v_add_f32_e32 v125, v125, v188
	v_cndmask_b32_e64 v188, 0, v114, s[10:11]
	v_add_f32_e32 v126, v126, v188
	v_cndmask_b32_e64 v188, 0, v115, s[10:11]
	v_cndmask_b32_e64 v112, 0, v112, s[12:13]
	v_cndmask_b32_e64 v113, 0, v113, s[12:13]
	v_cndmask_b32_e64 v114, 0, v114, s[12:13]
	v_cndmask_b32_e64 v115, 0, v115, s[12:13]
	v_add_f32_e32 v127, v127, v188
	v_add_f32_e32 v112, v128, v112
	v_add_f32_e32 v113, v129, v113
	v_add_f32_e32 v114, v130, v114
	v_add_f32_e32 v115, v131, v115
	ds_write2st64_b32 v205, v116, v117 offset1:1
	ds_write2st64_b32 v205, v118, v119 offset0:2 offset1:3
	ds_write2st64_b32 v205, v120, v121 offset0:4 offset1:5
	ds_write2st64_b32 v205, v122, v123 offset0:6 offset1:7
	ds_write2st64_b32 v205, v124, v125 offset0:8 offset1:9
	ds_write2st64_b32 v205, v126, v127 offset0:10 offset1:11
	ds_write2st64_b32 v205, v112, v113 offset0:12 offset1:13
	ds_write2st64_b32 v205, v114, v115 offset0:14 offset1:15
	s_waitcnt lgkmcnt(0)
	s_barrier
	ds_read2st64_b64 v[88:91], v200 offset1:8
	ds_read2st64_b64 v[220:223], v200 offset0:16 offset1:24
	ds_read2st64_b64 v[224:227], v200 offset0:32 offset1:40
	ds_read2st64_b64 v[228:231], v200 offset0:48 offset1:56
	v_mfma_f32_16x16x32_bf16 v[132:135], v[96:99], v[206:209], v[100:103]
	s_waitcnt lgkmcnt(3)
	v_add_f32_e32 v88, 0, v88
	v_add_f32_e32 v89, 0, v89
	v_add_f32_e32 v92, v88, v90
	v_add_f32_e32 v93, v89, v91
	s_waitcnt lgkmcnt(2)
	v_add_f32_e32 v88, v92, v220
	v_add_f32_e32 v89, v93, v221
	v_add_f32_e32 v92, v88, v222
	v_add_f32_e32 v93, v89, v223
	s_waitcnt lgkmcnt(1)
	v_add_f32_e32 v88, v92, v224
	v_add_f32_e32 v89, v93, v225
	v_add_f32_e32 v92, v88, v226
	v_add_f32_e32 v93, v89, v227
	s_waitcnt lgkmcnt(0)
	v_add_f32_e32 v88, v92, v228
	v_add_f32_e32 v89, v93, v229
	v_add_f32_e32 v88, v88, v230
	v_add_f32_e32 v89, v89, v231
	v_cvt_pk_bf16_f32 v90, v88, v89
	v_add_co_u32_e32 v88, vcc, s88, v182
	s_nop 1
	v_addc_co_u32_e32 v89, vcc, 0, v183, vcc
	global_store_dword v[88:89], v90, off nt
	s_cbranch_scc1 .LBB0_457
	s_lshl_b32 s18, s93, 22
	s_and_b32 s18, s18, 0x1000000
	s_add_u32 s18, s66, s18
	s_addc_u32 s33, s67, 0
	s_lshl_b32 s54, s91, 10
	s_and_b32 s54, s54, 0xc00
	s_add_u32 s18, s18, s54
	s_waitcnt vmcnt(17)
	ds_read_b64_tr_b16 v[12:13], v191
	s_addc_u32 s33, s33, 0
	s_lshl_b32 s54, s91, 1
	ds_read_b64_tr_b16 v[14:15], v193
	s_and_b32 s54, s54, -16
	s_waitcnt vmcnt(4)
	ds_read_b64_tr_b16 v[24:25], v194
	s_ashr_i32 s55, s54, 31
	ds_read_b64_tr_b16 v[26:27], v195
	s_lshl_b64 s[54:55], s[54:55], 1
	s_waitcnt lgkmcnt(0)
	s_add_u32 s66, s18, s54
	s_addc_u32 s67, s33, s55
	v_cndmask_b32_e64 v13, v25, v13, s[4:5]
	v_cndmask_b32_e64 v12, v24, v12, s[4:5]
	v_cndmask_b32_e64 v15, v27, v15, s[4:5]
	v_cndmask_b32_e64 v14, v26, v14, s[4:5]
	v_cvt_pk_bf16_f32 v4, v132, v133
	v_cvt_pk_bf16_f32 v5, v134, v135
	v_cvt_pk_bf16_f32 v6, v136, v137
	v_cvt_pk_bf16_f32 v7, v138, v139
	s_nop 0
	v_mfma_f32_16x16x32_bf16 v[8:11], v[44:47], v[4:7], 0
	v_mfma_f32_16x16x32_bf16 v[0:3], v[0:3], v[12:15], 0
	v_mfma_f32_16x16x32_bf16 v[16:19], v[52:55], v[4:7], 0
	s_nop 6
	v_cndmask_b32_e64 v12, 0, v0, s[6:7]
	v_add_f32_e32 v8, v8, v12
	v_mfma_f32_16x16x32_bf16 v[12:15], v[28:31], v[4:7], 0
	v_cndmask_b32_e64 v24, 0, v1, s[6:7]
	v_add_f32_e32 v9, v9, v24
	v_cndmask_b32_e64 v24, 0, v2, s[6:7]
	v_mfma_f32_16x16x32_bf16 v[4:7], v[20:23], v[4:7], 0
	v_cndmask_b32_e64 v20, 0, v3, s[6:7]
	v_add_f32_e32 v11, v11, v20
	v_cndmask_b32_e64 v20, 0, v0, s[8:9]
	v_add_f32_e32 v16, v16, v20
	v_cndmask_b32_e64 v20, 0, v1, s[8:9]
	v_add_f32_e32 v17, v17, v20
	v_cndmask_b32_e64 v20, 0, v2, s[8:9]
	v_add_f32_e32 v18, v18, v20
	v_cndmask_b32_e64 v20, 0, v3, s[8:9]
	v_add_f32_e32 v19, v19, v20
	v_cndmask_b32_e64 v20, 0, v0, s[10:11]
	v_add_f32_e32 v12, v12, v20
	v_cndmask_b32_e64 v20, 0, v1, s[10:11]
	v_add_f32_e32 v13, v13, v20
	v_cndmask_b32_e64 v20, 0, v2, s[10:11]
	v_add_f32_e32 v14, v14, v20
	v_cndmask_b32_e64 v20, 0, v3, s[10:11]
	v_cndmask_b32_e64 v0, 0, v0, s[12:13]
	v_cndmask_b32_e64 v1, 0, v1, s[12:13]
	v_cndmask_b32_e64 v2, 0, v2, s[12:13]
	v_cndmask_b32_e64 v3, 0, v3, s[12:13]
	v_add_f32_e32 v0, v4, v0
	v_add_f32_e32 v1, v5, v1
	v_add_f32_e32 v2, v6, v2
	v_add_f32_e32 v3, v7, v3
	v_add_u32_e32 v4, s68, v196
	v_add_f32_e32 v10, v10, v24
	v_add_f32_e32 v15, v15, v20
	ds_write2st64_b32 v4, v8, v9 offset0:128 offset1:129
	ds_write2st64_b32 v4, v10, v11 offset0:130 offset1:131
	ds_write2st64_b32 v4, v16, v17 offset0:132 offset1:133
	ds_write2st64_b32 v4, v18, v19 offset0:134 offset1:135
	ds_write2st64_b32 v4, v12, v13 offset0:136 offset1:137
	ds_write2st64_b32 v4, v14, v15 offset0:138 offset1:139
	ds_write2st64_b32 v4, v0, v1 offset0:140 offset1:141
	ds_write2st64_b32 v4, v2, v3 offset0:142 offset1:143
	s_waitcnt lgkmcnt(0)
	s_barrier
	ds_read2st64_b64 v[0:3], v197 offset0:64 offset1:72
	ds_read2st64_b64 v[4:7], v197 offset0:80 offset1:88
	s_waitcnt lgkmcnt(1)
	v_add_f32_e32 v0, 0, v0
	v_add_f32_e32 v1, 0, v1
	v_add_f32_e32 v0, v0, v2
	v_add_f32_e32 v8, v1, v3
	s_waitcnt lgkmcnt(0)
	v_add_f32_e32 v4, v0, v4
	ds_read2st64_b64 v[0:3], v197 offset0:96 offset1:104
	v_add_f32_e32 v5, v8, v5
	v_add_f32_e32 v8, v4, v6
	v_add_f32_e32 v9, v5, v7
	ds_read2st64_b64 v[4:7], v197 offset0:112 offset1:120
	s_waitcnt lgkmcnt(1)
	v_add_f32_e32 v0, v8, v0
	v_add_f32_e32 v1, v9, v1
	v_add_f32_e32 v0, v0, v2
	v_add_f32_e32 v1, v1, v3
	s_waitcnt lgkmcnt(0)
	v_add_f32_e32 v0, v0, v4
	v_add_f32_e32 v1, v1, v5
	v_add_f32_e32 v0, v0, v6
	v_add_f32_e32 v1, v1, v7
	v_cvt_pk_bf16_f32 v4, v0, v1
	v_lshl_add_u64 v[0:1], s[66:67], 0, v[146:147]
	v_lshlrev_b32_e32 v2, 1, v148
	v_mov_b32_e32 v3, v143
	v_lshl_add_u64 v[0:1], v[0:1], 0, v[2:3]
	v_add_co_u32_e32 v0, vcc, 0x1a7c0000, v0
	s_mov_b64 s[66:67], 0
	s_nop 0
	v_addc_co_u32_e32 v1, vcc, 0, v1, vcc
	global_store_dword v[0:1], v4, off nt
	s_barrier
.LBB0_459:
	s_and_b64 vcc, exec, s[66:67]
	s_cbranch_vccz .LBB0_454
	s_lshl_b32 s18, s90, 10
	s_and_b32 s18, s18, 0x1000
	v_add_u32_e32 v0, s18, v199
	v_mad_u64_u32 v[0:1], s[54:55], v0, s89, 0
	s_add_u32 s54, s60, s95
	v_or_b32_e32 v0, v162, v0
	s_addc_u32 s55, s61, 0
	v_lshl_add_u64 v[170:171], s[54:55], 0, v[0:1]
	s_mov_b64 s[54:55], s[0:1]
	s_load_dwordx2 s[60:61], s[54:55], 0x80
	s_lshl_b32 s18, s94, 1
	v_lshl_add_u64 v[168:169], v[160:161], 0, s[64:65]
	v_lshl_add_u64 v[166:167], v[158:159], 0, s[62:63]
	s_mov_b64 s[66:67], 0xe601000
	s_waitcnt lgkmcnt(0)
	s_add_u32 s18, s60, s18
	s_addc_u32 s33, s61, 0
	s_add_u32 s54, s18, s26
	s_addc_u32 s55, s33, s27
	s_lshl_b32 s18, s93, 10
	s_and_b32 s64, s18, 0x1000
	s_lshl_b32 s18, s91, 9
	v_add_u32_e32 v2, s64, v198
	v_mov_b64_e32 v[0:1], s[60:61]
	s_and_b32 s65, s18, 0x600
	v_mad_u64_u32 v[0:1], s[62:63], v2, s89, v[0:1]
	s_lshl_b32 s18, s65, 1
	v_lshl_add_u64 v[0:1], v[0:1], 0, s[18:19]
	s_lshl_b32 s18, s91, 1
	s_and_b32 s62, s18, -16
	s_ashr_i32 s63, s62, 31
	s_lshl_b32 s18, s92, 10
	v_lshl_add_u64 v[0:1], s[62:63], 1, v[0:1]
	s_add_u32 s18, s60, s18
	s_waitcnt vmcnt(8)
	v_lshl_add_u64 v[36:37], v[0:1], 0, v[142:143]
	s_addc_u32 s33, s61, 0
	v_lshl_add_u64 v[172:173], v[36:37], 0, s[66:67]
	s_add_u32 s66, s18, s28
	s_mov_b32 s18, 0xe601000
	v_add_co_u32_e32 v0, vcc, s18, v36
	s_waitcnt vmcnt(7)
	v_lshl_add_u64 v[44:45], s[54:55], 0, v[140:141]
	v_addc_co_u32_e32 v1, vcc, 0, v37, vcc
	global_load_dwordx4 v[84:87], v[0:1], off nt
	v_add_co_u32_e32 v0, vcc, s78, v44
	s_addc_u32 s67, s33, s29
	s_nop 0
	v_addc_co_u32_e32 v1, vcc, 0, v45, vcc
	v_add_co_u32_e32 v16, vcc, s79, v44
	s_waitcnt vmcnt(5)
	v_lshl_add_u64 v[32:33], s[66:67], 0, v[144:145]
	v_addc_co_u32_e32 v17, vcc, 0, v45, vcc
	v_lshl_add_u64 v[178:179], v[32:33], 0, s[36:37]
	v_add_co_u32_e32 v32, vcc, s80, v32
	s_mov_b32 s18, 0xe6c1000
	s_nop 0
	v_addc_co_u32_e32 v33, vcc, 0, v33, vcc
	v_add_co_u32_e32 v36, vcc, s18, v36
	s_mov_b32 s18, 0x16708000
	s_nop 0
	v_addc_co_u32_e32 v37, vcc, 0, v37, vcc
	v_add_co_u32_e32 v38, vcc, s81, v44
	v_lshl_add_u64 v[174:175], v[44:45], 0, s[30:31]
	s_nop 0
	v_addc_co_u32_e32 v39, vcc, 0, v45, vcc
	global_load_dwordx4 v[12:15], v[0:1], off
	global_load_dwordx4 v[8:11], v[174:175], off offset:1024
	global_load_dwordx4 v[4:7], v[174:175], off offset:2048
	s_nop 0
	global_load_dwordx4 v[0:3], v[174:175], off offset:3072
	v_lshl_add_u64 v[176:177], v[44:45], 0, s[34:35]
	global_load_dwordx4 v[24:27], v[16:17], off
	global_load_dwordx4 v[28:31], v[176:177], off offset:1024
	global_load_dwordx4 v[20:23], v[176:177], off offset:2048
	s_nop 0
	global_load_dwordx4 v[16:19], v[176:177], off offset:3072
	global_load_dwordx4 v[40:43], v[32:33], off
	s_nop 0
	global_load_dwordx4 v[32:35], v[178:179], off offset:64
	global_load_dwordx4 v[80:83], v[36:37], off nt
	v_lshl_add_u64 v[36:37], v[44:45], 0, s[38:39]
	v_lshl_add_u64 v[52:53], v[44:45], 0, s[40:41]
	v_add_co_u32_e32 v44, vcc, s18, v44
	global_load_dwordx4 v[64:67], v[38:39], off
	global_load_dwordx4 v[68:71], v[36:37], off offset:1024
	global_load_dwordx4 v[56:59], v[36:37], off offset:2048
	s_nop 0
	global_load_dwordx4 v[36:39], v[36:37], off offset:3072
	v_addc_co_u32_e32 v45, vcc, 0, v45, vcc
	global_load_dwordx4 v[44:47], v[44:45], off
	s_nop 0
	global_load_dwordx4 v[60:63], v[52:53], off offset:1024
	global_load_dwordx4 v[48:51], v[52:53], off offset:2048
	s_nop 0
	global_load_dwordx4 v[52:55], v[52:53], off offset:3072
	s_nop 0
	global_load_dwordx4 v[76:79], v[178:179], off offset:1024
	global_load_dwordx4 v[72:75], v[178:179], off offset:1088
	v_mov_b32_e32 v128, 0
	v_add_u32_e32 v88, s70, v140
	s_mov_b32 s18, -3
	s_movk_i32 s66, 0x800
	v_mov_b32_e32 v129, v128
	v_mov_b32_e32 v130, v128
	v_mov_b32_e32 v131, v128
	v_mov_b32_e32 v132, v128
	v_mov_b32_e32 v133, v128
	v_mov_b32_e32 v134, v128
	v_mov_b32_e32 v135, v128
	s_waitcnt vmcnt(21)
	ds_write_b128 v88, v[84:87]
	s_waitcnt lgkmcnt(0)
	s_barrier
.LBB0_461:
	v_lshl_add_u64 v[188:189], s[60:61], 0, v[170:171]
	s_mov_b32 s33, 0xe781000
	v_add_co_u32_e32 v84, vcc, s33, v188
	v_lshl_add_u64 v[200:201], s[60:61], 0, v[166:167]
	s_nop 0
	v_addc_co_u32_e32 v85, vcc, 0, v189, vcc
	v_add_co_u32_e32 v86, vcc, s82, v200
	v_lshl_add_u64 v[202:203], s[60:61], 0, v[168:169]
	s_nop 0
	v_addc_co_u32_e32 v87, vcc, 0, v201, vcc
	global_load_dwordx4 v[136:139], v[84:85], off nt
	global_load_dwordx4 v[124:127], v[86:87], off
	global_load_dwordx4 v[112:115], v[86:87], off offset:1024
	global_load_dwordx4 v[108:111], v[86:87], off offset:2048
	v_add_co_u32_e32 v84, vcc, s83, v200
	s_add_i32 s33, s18, 3
	s_nop 0
	v_addc_co_u32_e32 v85, vcc, 0, v201, vcc
	global_load_dwordx4 v[104:107], v[86:87], off offset:3072
	global_load_dwordx4 v[100:103], v[84:85], off
	global_load_dwordx4 v[92:95], v[84:85], off offset:1024
	global_load_dwordx4 v[96:99], v[84:85], off offset:2048
	global_load_dwordx4 v[88:91], v[84:85], off offset:3072
	global_load_dwordx4 v[120:123], v[202:203], off offset:-1024
	global_load_dwordx4 v[116:119], v[202:203], off offset:-960
	s_and_b32 s54, s33, 1
	s_lshl_b32 s55, s54, 15
	s_lshl_b32 s54, s54, 11
	s_add_i32 s54, s69, s54
	v_add_u32_e32 v204, s54, v163
	ds_read_b64_tr_b16 v[84:85], v204
	v_add_u32_e32 v205, 0x80, v204
	ds_read_b64_tr_b16 v[86:87], v205
	v_add_u32_e32 v206, 0x400, v204
	ds_read_b64_tr_b16 v[184:185], v206
	v_add_u32_e32 v207, 0x480, v204
	ds_read_b64_tr_b16 v[186:187], v207
	s_waitcnt lgkmcnt(0)
	s_add_i32 s54, s55, 0
	v_cvt_pk_bf16_f32 v180, v128, v129
	v_cvt_pk_bf16_f32 v181, v130, v131
	v_cvt_pk_bf16_f32 v182, v132, v133
	v_cvt_pk_bf16_f32 v183, v134, v135
	v_lshlrev_b32_e32 v208, 2, v149
	s_waitcnt vmcnt(31)
	v_mfma_f32_16x16x32_bf16 v[12:15], v[12:15], v[180:183], 0
	s_add_i32 s55, s68, s54
	s_waitcnt vmcnt(22)
	v_pk_mul_f32 v[34:35], v[134:135], v[34:35]
	v_pk_mul_f32 v[32:33], v[132:133], v[32:33]
	v_mfma_f32_16x16x32_bf16 v[8:11], v[8:11], v[180:183], 0
	v_lshlrev_b32_e32 v209, 2, v190
	v_pk_mul_f32 v[42:43], v[130:131], v[42:43]
	v_pk_mul_f32 v[40:41], v[128:129], v[40:41]
	v_mfma_f32_16x16x32_bf16 v[4:7], v[4:7], v[180:183], 0
	s_add_i32 s18, s18, 4
	s_and_b32 s18, s18, 1
	v_mfma_f32_16x16x32_bf16 v[0:3], v[0:3], v[180:183], 0
	v_add_u32_e32 v182, s55, v208
	s_add_i32 s55, s66, 0xfffff800
	s_andn2_b32 s55, 0x800, s55
	s_add_i32 s55, s71, s55
	ds_write2st64_b32 v182, v12, v13 offset1:1
	ds_write2st64_b32 v182, v14, v15 offset0:2 offset1:3
	ds_write2st64_b32 v182, v8, v9 offset0:4 offset1:5
	ds_write2st64_b32 v182, v10, v11 offset0:6 offset1:7
	ds_write2st64_b32 v182, v4, v5 offset0:8 offset1:9
	ds_write2st64_b32 v182, v6, v7 offset0:10 offset1:11
	ds_write2st64_b32 v182, v0, v1 offset0:12 offset1:13
	ds_write2st64_b32 v182, v2, v3 offset0:14 offset1:15
	v_mfma_f32_16x16x32_bf16 v[0:3], v[20:23], v[84:87], v[32:35]
	v_add_u32_e32 v4, s55, v140
	v_add_u32_e32 v4, 0xffffe800, v4
	v_add_u32_e32 v183, s54, v209
	s_waitcnt vmcnt(21)
	ds_write_b128 v4, v[80:83]
	s_waitcnt lgkmcnt(0)
	s_barrier
	ds_read2st64_b64 v[4:7], v183 offset1:8
	v_mfma_f32_16x16x32_bf16 v[80:83], v[16:19], v[184:187], v[0:3]
	v_lshl_add_u64 v[180:181], s[60:61], 0, v[164:165]
	s_mov_b32 s54, 0xe841000
	s_waitcnt lgkmcnt(0)
	v_add_f32_e32 v4, 0, v4
	ds_read2st64_b64 v[0:3], v183 offset0:16 offset1:24
	v_add_f32_e32 v5, 0, v5
	v_add_f32_e32 v4, v4, v6
	v_add_f32_e32 v8, v5, v7
	v_mfma_f32_16x16x32_bf16 v[12:15], v[24:27], v[84:87], v[40:43]
	s_waitcnt lgkmcnt(0)
	v_add_f32_e32 v0, v4, v0
	ds_read2st64_b64 v[4:7], v183 offset0:32 offset1:40
	v_add_f32_e32 v1, v8, v1
	v_add_f32_e32 v8, v0, v2
	v_add_f32_e32 v9, v1, v3
	ds_read2st64_b64 v[0:3], v183 offset0:48 offset1:56
	s_waitcnt lgkmcnt(1)
	v_add_f32_e32 v4, v8, v4
	v_add_f32_e32 v5, v9, v5
	v_add_f32_e32 v4, v4, v6
	v_add_f32_e32 v5, v5, v7
	s_waitcnt lgkmcnt(0)
	v_add_f32_e32 v0, v4, v0
	v_add_f32_e32 v1, v5, v1
	v_add_f32_e32 v0, v0, v2
	v_add_f32_e32 v1, v1, v3
	v_cvt_pk_bf16_f32 v2, v0, v1
	v_add_co_u32_e32 v0, vcc, s84, v180
	v_mfma_f32_16x16x32_bf16 v[128:131], v[28:31], v[184:187], v[12:15]
	s_nop 0
	v_addc_co_u32_e32 v1, vcc, 0, v181, vcc
	global_store_dword v[0:1], v2, off nt
	v_add_co_u32_e32 v0, vcc, s54, v188
	s_lshl_b32 s54, s18, 15
	s_nop 0
	v_addc_co_u32_e32 v1, vcc, 0, v189, vcc
	v_add_co_u32_e32 v2, vcc, s85, v200
	s_lshl_b32 s18, s18, 11
	s_nop 0
	v_addc_co_u32_e32 v3, vcc, 0, v201, vcc
	v_add_co_u32_e32 v16, vcc, s86, v200
	global_load_dwordx4 v[84:87], v[0:1], off nt
	global_load_dwordx4 v[12:15], v[2:3], off
	global_load_dwordx4 v[8:11], v[2:3], off offset:1024
	global_load_dwordx4 v[4:7], v[2:3], off offset:2048
	v_addc_co_u32_e32 v17, vcc, 0, v201, vcc
	global_load_dwordx4 v[0:3], v[2:3], off offset:3072
	s_nop 0
	global_load_dwordx4 v[24:27], v[16:17], off
	global_load_dwordx4 v[28:31], v[16:17], off offset:1024
	global_load_dwordx4 v[20:23], v[16:17], off offset:2048
	s_nop 0
	global_load_dwordx4 v[16:19], v[16:17], off offset:3072
	s_nop 0
	global_load_dwordx4 v[40:43], v[202:203], off
	global_load_dwordx4 v[32:35], v[202:203], off offset:64
	s_add_i32 s18, s69, s18
	v_add_u32_e32 v186, s18, v163
	ds_read_b64_tr_b16 v[132:133], v186
	v_add_u32_e32 v134, 0x80, v186
	ds_read_b64_tr_b16 v[134:135], v134
	v_add_u32_e32 v184, 0x400, v186
	ds_read_b64_tr_b16 v[184:185], v184
	v_add_u32_e32 v186, 0x480, v186
	ds_read_b64_tr_b16 v[186:187], v186
	s_waitcnt lgkmcnt(0)
	s_waitcnt vmcnt(24)
	v_pk_mul_f32 v[78:79], v[78:79], v[130:131]
	v_pk_mul_f32 v[76:77], v[76:77], v[128:129]
	v_cvt_pk_bf16_f32 v200, v128, v129
	v_cvt_pk_bf16_f32 v201, v130, v131
	v_cvt_pk_bf16_f32 v202, v80, v81
	v_cvt_pk_bf16_f32 v203, v82, v83
	s_add_i32 s18, s54, 0
	v_mfma_f32_16x16x32_bf16 v[64:67], v[64:67], v[200:203], 0
	s_add_i32 s54, s68, s18
	s_waitcnt vmcnt(23)
	v_pk_mul_f32 v[72:73], v[72:73], v[80:81]
	v_add_u32_e32 v80, s54, v208
	v_mfma_f32_16x16x32_bf16 v[68:71], v[68:71], v[200:203], 0
	s_andn2_b32 s54, 0x800, s66
	v_pk_mul_f32 v[74:75], v[74:75], v[82:83]
	s_add_i32 s54, s71, s54
	v_mfma_f32_16x16x32_bf16 v[36:39], v[36:39], v[200:203], 0
	ds_write2st64_b32 v80, v64, v65 offset1:1
	ds_write2st64_b32 v80, v66, v67 offset0:2 offset1:3
	s_nop 1
	ds_write2st64_b32 v80, v68, v69 offset0:4 offset1:5
	v_mfma_f32_16x16x32_bf16 v[44:47], v[44:47], v[132:135], v[76:79]
	v_mfma_f32_16x16x32_bf16 v[56:59], v[56:59], v[200:203], 0
	ds_write2st64_b32 v80, v70, v71 offset0:6 offset1:7
	s_nop 6
	ds_write2st64_b32 v80, v56, v57 offset0:8 offset1:9
	ds_write2st64_b32 v80, v58, v59 offset0:10 offset1:11
	v_mfma_f32_16x16x32_bf16 v[200:203], v[60:63], v[184:187], v[44:47]
	ds_write2st64_b32 v80, v36, v37 offset0:12 offset1:13
	ds_write2st64_b32 v80, v38, v39 offset0:14 offset1:15
	s_nop 0
	v_add_u32_e32 v44, s54, v140
	v_mfma_f32_16x16x32_bf16 v[36:39], v[48:51], v[132:135], v[72:75]
	v_add_u32_e32 v44, 0xffffe800, v44
	v_add_u32_e32 v48, s18, v209
	s_waitcnt vmcnt(22)
	ds_write_b128 v44, v[136:139]
	s_waitcnt lgkmcnt(0)
	s_barrier
	ds_read2st64_b64 v[44:47], v48 offset1:8
	v_mfma_f32_16x16x32_bf16 v[136:139], v[52:55], v[184:187], v[36:39]
	s_min_u32 s18, s33, 59
	s_add_i32 s54, s18, 4
	s_mul_i32 s18, s54, 0xc0000
	ds_read2st64_b64 v[36:39], v48 offset0:16 offset1:24
	s_waitcnt lgkmcnt(1)
	v_add_f32_e32 v44, 0, v44
	v_add_f32_e32 v45, 0, v45
	v_add_f32_e32 v44, v44, v46
	v_add_f32_e32 v49, v45, v47
	s_waitcnt lgkmcnt(0)
	v_add_f32_e32 v36, v44, v36
	ds_read2st64_b64 v[44:47], v48 offset0:32 offset1:40
	v_add_f32_e32 v37, v49, v37
	v_add_f32_e32 v49, v36, v38
	v_add_f32_e32 v50, v37, v39
	ds_read2st64_b64 v[36:39], v48 offset0:48 offset1:56
	s_waitcnt lgkmcnt(1)
	v_add_f32_e32 v44, v49, v44
	v_add_f32_e32 v45, v50, v45
	v_add_f32_e32 v44, v44, v46
	v_add_f32_e32 v45, v45, v47
	s_waitcnt lgkmcnt(0)
	v_add_f32_e32 v36, v44, v36
	v_add_f32_e32 v37, v45, v37
	v_add_f32_e32 v36, v36, v38
	v_add_f32_e32 v37, v37, v39
	v_cvt_pk_bf16_f32 v38, v36, v37
	v_add_co_u32_e32 v36, vcc, s87, v180
	s_nop 1
	v_addc_co_u32_e32 v37, vcc, 0, v181, vcc
	global_store_dword v[36:37], v38, off nt
	v_lshl_add_u64 v[36:37], v[172:173], 0, s[18:19]
	s_lshl_b32 s18, s54, 15
	v_lshl_add_u64 v[38:39], v[174:175], 0, s[18:19]
	v_lshl_add_u64 v[52:53], v[176:177], 0, s[18:19]
	s_lshl_b32 s18, s54, 10
	global_load_dwordx4 v[80:83], v[36:37], off nt
	global_load_dwordx4 v[64:67], v[38:39], off
	global_load_dwordx4 v[68:71], v[38:39], off offset:1024
	global_load_dwordx4 v[56:59], v[38:39], off offset:2048
	s_nop 0
	global_load_dwordx4 v[36:39], v[38:39], off offset:3072
	s_nop 0
	global_load_dwordx4 v[44:47], v[52:53], off
	global_load_dwordx4 v[60:63], v[52:53], off offset:1024
	global_load_dwordx4 v[48:51], v[52:53], off offset:2048
	v_lshl_add_u64 v[72:73], v[178:179], 0, s[18:19]
	global_load_dwordx4 v[52:55], v[52:53], off offset:3072
	s_nop 0
	global_load_dwordx4 v[76:79], v[72:73], off
	s_nop 0
	global_load_dwordx4 v[72:75], v[72:73], off offset:64
	ds_read_b64_tr_b16 v[128:129], v204
	ds_read_b64_tr_b16 v[130:131], v205
	ds_read_b64_tr_b16 v[132:133], v206
	ds_read_b64_tr_b16 v[134:135], v207
	s_waitcnt lgkmcnt(0)
	s_waitcnt vmcnt(25)
	v_pk_mul_f32 v[122:123], v[122:123], v[202:203]
	v_pk_mul_f32 v[120:121], v[120:121], v[200:201]
	v_cvt_pk_bf16_f32 v184, v200, v201
	v_cvt_pk_bf16_f32 v185, v202, v203
	v_cvt_pk_bf16_f32 v186, v136, v137
	v_cvt_pk_bf16_f32 v187, v138, v139
	s_add_i32 s54, s66, 0x800
	v_mfma_f32_16x16x32_bf16 v[124:127], v[124:127], v[184:187], 0
	s_andn2_b32 s54, 0x800, s54
	s_waitcnt vmcnt(24)
	v_pk_mul_f32 v[118:119], v[118:119], v[138:139]
	v_pk_mul_f32 v[116:117], v[116:117], v[136:137]
	v_mfma_f32_16x16x32_bf16 v[100:103], v[100:103], v[128:131], v[120:123]
	s_add_i32 s54, s71, s54
	v_add_co_u32_e32 v136, vcc, s88, v180
	v_mfma_f32_16x16x32_bf16 v[112:115], v[112:115], v[184:187], 0
	s_addk_i32 s66, 0x1800
	v_addc_co_u32_e32 v137, vcc, 0, v181, vcc
	v_mfma_f32_16x16x32_bf16 v[96:99], v[96:99], v[128:131], v[116:119]
	v_lshl_add_u64 v[164:165], v[164:165], 0, s[42:43]
	v_lshl_add_u64 v[166:167], v[166:167], 0, s[48:49]
	v_lshl_add_u64 v[168:169], v[168:169], 0, s[50:51]
	v_add_u32_e32 v116, s54, v140
	v_mfma_f32_16x16x32_bf16 v[108:111], v[108:111], v[184:187], 0
	v_add_u32_e32 v116, 0xffffe800, v116
	v_lshl_add_u64 v[170:171], v[170:171], 0, s[58:59]
	s_mov_b32 s18, s33
	v_mfma_f32_16x16x32_bf16 v[104:107], v[104:107], v[184:187], 0
	ds_write2st64_b32 v182, v124, v125 offset1:1
	ds_write2st64_b32 v182, v126, v127 offset0:2 offset1:3
	ds_write2st64_b32 v182, v112, v113 offset0:4 offset1:5
	ds_write2st64_b32 v182, v114, v115 offset0:6 offset1:7
	ds_write2st64_b32 v182, v108, v109 offset0:8 offset1:9
	ds_write2st64_b32 v182, v110, v111 offset0:10 offset1:11
	s_nop 1
	ds_write2st64_b32 v182, v104, v105 offset0:12 offset1:13
	ds_write2st64_b32 v182, v106, v107 offset0:14 offset1:15
	s_waitcnt vmcnt(22)
	ds_write_b128 v116, v[84:87]
	s_waitcnt lgkmcnt(0)
	s_barrier
	v_mfma_f32_16x16x32_bf16 v[128:131], v[92:95], v[132:135], v[100:103]
	ds_read2st64_b64 v[92:95], v183 offset1:8
	s_cmp_lt_u32 s33, 60
	v_mfma_f32_16x16x32_bf16 v[132:135], v[88:91], v[132:135], v[96:99]
	ds_read2st64_b64 v[88:91], v183 offset0:16 offset1:24
	s_nop 1
	ds_read2st64_b64 v[96:99], v183 offset0:32 offset1:40
	ds_read2st64_b64 v[100:103], v183 offset0:48 offset1:56
	s_waitcnt lgkmcnt(3)
	v_add_f32_e32 v92, 0, v92
	v_add_f32_e32 v93, 0, v93
	v_add_f32_e32 v92, v92, v94
	v_add_f32_e32 v93, v93, v95
	s_waitcnt lgkmcnt(2)
	v_add_f32_e32 v88, v92, v88
	v_add_f32_e32 v89, v93, v89
	v_add_f32_e32 v88, v88, v90
	v_add_f32_e32 v89, v89, v91
	s_waitcnt lgkmcnt(1)
	v_add_f32_e32 v88, v88, v96
	v_add_f32_e32 v89, v89, v97
	v_add_f32_e32 v88, v88, v98
	v_add_f32_e32 v89, v89, v99
	s_waitcnt lgkmcnt(0)
	v_add_f32_e32 v88, v88, v100
	v_add_f32_e32 v89, v89, v101
	v_add_f32_e32 v88, v88, v102
	v_add_f32_e32 v89, v89, v103
	v_cvt_pk_bf16_f32 v88, v88, v89
	global_store_dword v[136:137], v88, off nt
	s_cbranch_scc1 .LBB0_461
	s_waitcnt vmcnt(15)
	ds_read_b64_tr_b16 v[16:17], v191
	s_lshl_b32 s18, s64, 12
	ds_read_b64_tr_b16 v[16:17], v193
	s_add_u32 s18, s60, s18
	ds_read_b64_tr_b16 v[16:17], v194
	s_addc_u32 s33, s61, 0
	s_lshl_b32 s54, s65, 1
	ds_read_b64_tr_b16 v[16:17], v195
	s_add_u32 s18, s18, s54
	s_waitcnt lgkmcnt(0)
	s_addc_u32 s33, s33, 0
	s_lshl_b64 s[54:55], s[62:63], 1
	s_add_u32 s54, s18, s54
	s_addc_u32 s55, s33, s55
	v_cvt_pk_bf16_f32 v16, v128, v129
	v_cvt_pk_bf16_f32 v17, v130, v131
	v_cvt_pk_bf16_f32 v18, v132, v133
	v_cvt_pk_bf16_f32 v19, v134, v135
	v_add_u32_e32 v20, s68, v196
	v_mfma_f32_16x16x32_bf16 v[12:15], v[12:15], v[16:19], 0
	v_mfma_f32_16x16x32_bf16 v[8:11], v[8:11], v[16:19], 0
	s_nop 6
	ds_write2st64_b32 v20, v12, v13 offset0:128 offset1:129
	ds_write2st64_b32 v20, v14, v15 offset0:130 offset1:131
	ds_write2st64_b32 v20, v8, v9 offset0:132 offset1:133
	v_mfma_f32_16x16x32_bf16 v[0:3], v[0:3], v[16:19], 0
	v_mfma_f32_16x16x32_bf16 v[4:7], v[4:7], v[16:19], 0
	ds_write2st64_b32 v20, v10, v11 offset0:134 offset1:135
	s_nop 6
	ds_write2st64_b32 v20, v4, v5 offset0:136 offset1:137
	ds_write2st64_b32 v20, v6, v7 offset0:138 offset1:139
	ds_write2st64_b32 v20, v0, v1 offset0:140 offset1:141
	ds_write2st64_b32 v20, v2, v3 offset0:142 offset1:143
	v_add_u32_e32 v0, s72, v140
	ds_write_b128 v0, v[84:87]
	s_waitcnt lgkmcnt(0)
	s_barrier
	ds_read2st64_b64 v[0:3], v197 offset0:64 offset1:72
	ds_read2st64_b64 v[4:7], v197 offset0:80 offset1:88
	s_waitcnt lgkmcnt(1)
	v_add_f32_e32 v0, 0, v0
	v_add_f32_e32 v1, 0, v1
	v_add_f32_e32 v0, v0, v2
	v_add_f32_e32 v8, v1, v3
	s_waitcnt lgkmcnt(0)
	v_add_f32_e32 v4, v0, v4
	ds_read2st64_b64 v[0:3], v197 offset0:96 offset1:104
	v_add_f32_e32 v5, v8, v5
	v_add_f32_e32 v8, v4, v6
	v_add_f32_e32 v9, v5, v7
	ds_read2st64_b64 v[4:7], v197 offset0:112 offset1:120
	s_waitcnt lgkmcnt(1)
	v_add_f32_e32 v0, v8, v0
	v_add_f32_e32 v1, v9, v1
	v_add_f32_e32 v0, v0, v2
	v_add_f32_e32 v1, v1, v3
	s_waitcnt lgkmcnt(0)
	v_add_f32_e32 v0, v0, v4
	v_add_f32_e32 v1, v1, v5
	v_add_f32_e32 v0, v0, v6
	v_add_f32_e32 v1, v1, v7
	v_cvt_pk_bf16_f32 v4, v0, v1
	v_lshl_add_u64 v[0:1], s[54:55], 0, v[146:147]
	v_lshlrev_b32_e32 v2, 1, v148
	v_mov_b32_e32 v3, v143
	v_lshl_add_u64 v[0:1], v[0:1], 0, v[2:3]
	v_add_co_u32_e32 v0, vcc, 0x1a7c0000, v0
	s_nop 1
	v_addc_co_u32_e32 v1, vcc, 0, v1, vcc
	global_store_dword v[0:1], v4, off nt
	s_barrier
	s_branch .LBB0_454
